# RWKV scan: original lane mapping on all 8 waves, operands reloaded right after use, y reduction rides with next step sa reduction; S5 scan reads hoisted
# baseline (speedup 1.0000x reference)
.LBB0_268:
	v_lshlrev_b32_e32 v136, 16, v124
	v_and_b32_e32 v137, 0xffff0000, v124
	v_lshlrev_b32_e32 v138, 16, v128
	v_and_b32_e32 v139, 0xffff0000, v128
	v_lshlrev_b32_e32 v124, 16, v125
	v_and_b32_e32 v125, 0xffff0000, v125
	v_lshlrev_b32_e32 v128, 16, v129
	v_and_b32_e32 v129, 0xffff0000, v129
	v_pk_add_f32 v[138:139], v[138:139], v[136:137] neg_lo:[0,1] neg_hi:[0,1]
	v_pk_add_f32 v[128:129], v[128:129], v[124:125] neg_lo:[0,1] neg_hi:[0,1]
	v_pk_fma_f32 v[136:137], v[12:13], v[138:139], v[136:137]
	v_pk_fma_f32 v[138:139], v[14:15], v[128:129], v[124:125]
	v_lshlrev_b32_e32 v124, 16, v126
	v_and_b32_e32 v125, 0xffff0000, v126
	v_lshlrev_b32_e32 v128, 16, v130
	v_and_b32_e32 v129, 0xffff0000, v130
	v_pk_add_f32 v[128:129], v[128:129], v[124:125] neg_lo:[0,1] neg_hi:[0,1]
	v_lshlrev_b32_e32 v126, 16, v127
	v_pk_fma_f32 v[124:125], v[8:9], v[128:129], v[124:125]
	v_and_b32_e32 v127, 0xffff0000, v127
	v_lshlrev_b32_e32 v128, 16, v131
	v_and_b32_e32 v129, 0xffff0000, v131
	v_pk_add_f32 v[128:129], v[128:129], v[126:127] neg_lo:[0,1] neg_hi:[0,1]
	v_lshlrev_b32_e32 v130, 16, v116
	v_pk_fma_f32 v[126:127], v[10:11], v[128:129], v[126:127]
	v_lshlrev_b32_e32 v128, 16, v112
	v_and_b32_e32 v129, 0xffff0000, v112
	v_and_b32_e32 v131, 0xffff0000, v116
	v_lshlrev_b32_e32 v112, 16, v113
	v_and_b32_e32 v113, 0xffff0000, v113
	v_lshlrev_b32_e32 v116, 16, v117
	v_and_b32_e32 v117, 0xffff0000, v117
	v_pk_add_f32 v[130:131], v[130:131], v[128:129] neg_lo:[0,1] neg_hi:[0,1]
	v_pk_add_f32 v[116:117], v[116:117], v[112:113] neg_lo:[0,1] neg_hi:[0,1]
	v_pk_fma_f32 v[142:143], v[36:37], v[130:131], v[128:129]
	v_lshlrev_b32_e32 v128, 16, v132
	v_and_b32_e32 v129, 0xffff0000, v132
	v_pk_fma_f32 v[116:117], v[38:39], v[116:117], v[112:113]
	v_lshlrev_b32_e32 v130, 16, v133
	v_and_b32_e32 v131, 0xffff0000, v133
	v_lshlrev_b32_e32 v112, 16, v114
	v_and_b32_e32 v113, 0xffff0000, v114
	v_lshlrev_b32_e32 v132, 16, v118
	v_and_b32_e32 v133, 0xffff0000, v118
	v_pk_add_f32 v[132:133], v[132:133], v[112:113] neg_lo:[0,1] neg_hi:[0,1]
	v_lshlrev_b32_e32 v114, 16, v119
	v_pk_fma_f32 v[146:147], v[32:33], v[132:133], v[112:113]
	v_lshlrev_b32_e32 v112, 16, v115
	v_and_b32_e32 v113, 0xffff0000, v115
	v_and_b32_e32 v115, 0xffff0000, v119
	v_pk_add_f32 v[114:115], v[114:115], v[112:113] neg_lo:[0,1] neg_hi:[0,1]
	v_pk_mul_f32 v[140:141], v[28:29], v[142:143]
	v_pk_fma_f32 v[118:119], v[34:35], v[114:115], v[112:113]
	v_pk_add_f32 v[112:113], v[128:129], -1.0 op_sel_hi:[1,0]
	v_lshlrev_b32_e32 v132, 16, v134
	v_pk_fma_f32 v[112:113], v[44:45], v[112:113], 1.0 op_sel_hi:[1,1,0]
	v_and_b32_e32 v133, 0xffff0000, v134
	v_pk_mul_f32 v[112:113], v[112:113], v[142:143]
	v_pk_mul_f32 v[142:143], v[30:31], v[116:117]
	v_pk_mul_f32 v[114:115], v[136:137], v[112:113]
	v_pk_mul_f32 v[148:149], v[140:141], v[140:141]
	v_fma_f32 v158, v4, v114, 0
	v_fmac_f32_e32 v158, v5, v115
	v_pk_add_f32 v[114:115], v[130:131], -1.0 op_sel_hi:[1,0]
	v_lshlrev_b32_e32 v134, 16, v135
	v_pk_fma_f32 v[114:115], v[46:47], v[114:115], 1.0 op_sel_hi:[1,1,0]
	v_and_b32_e32 v135, 0xffff0000, v135
	v_pk_mul_f32 v[114:115], v[114:115], v[116:117]
	v_pk_mul_f32 v[150:151], v[142:143], v[142:143]
	v_pk_mul_f32 v[116:117], v[138:139], v[114:115]
	v_add_f32_e32 v148, v148, v149
	v_fmac_f32_e32 v158, v6, v116
	v_fmac_f32_e32 v158, v7, v117
	v_pk_add_f32 v[116:117], v[132:133], -1.0 op_sel_hi:[1,0]
	v_pk_mul_f32 v[144:145], v[24:25], v[146:147]
	v_pk_fma_f32 v[116:117], v[40:41], v[116:117], 1.0 op_sel_hi:[1,1,0]
	v_pk_add_f32 v[154:155], v[134:135], -1.0 op_sel_hi:[1,0]
	v_pk_mul_f32 v[116:117], v[116:117], v[146:147]
	v_add_f32_e32 v148, v150, v148
	v_pk_mul_f32 v[146:147], v[124:125], v[116:117]
	v_pk_mul_f32 v[152:153], v[144:145], v[144:145]
	v_fmac_f32_e32 v158, v0, v146
	v_add_f32_e32 v148, v151, v148
	v_pk_fma_f32 v[150:151], v[42:43], v[154:155], 1.0 op_sel_hi:[1,1,0]
	v_fmac_f32_e32 v158, v1, v147
	v_pk_mul_f32 v[146:147], v[26:27], v[118:119]
	v_add_f32_e32 v148, v152, v148
	v_pk_mul_f32 v[118:119], v[150:151], v[118:119]
	v_pk_mul_f32 v[156:157], v[146:147], v[146:147]
	v_add_f32_e32 v148, v153, v148
	v_pk_mul_f32 v[150:151], v[126:127], v[118:119]
	v_add_f32_e32 v148, v156, v148
	v_fmac_f32_e32 v158, v2, v150
	v_add_f32_e32 v148, v157, v148
	v_fmac_f32_e32 v158, v3, v151
	s_nop 0
	v_add_f32_dpp v148, v148, v148 quad_perm:[1,0,3,2] row_mask:0xf bank_mask:0xf bound_ctrl:1
	v_add_f32_dpp v150, v158, v158 quad_perm:[1,0,3,2] row_mask:0xf bank_mask:0xf bound_ctrl:1
	s_nop 0
	v_add_f32_dpp v148, v148, v148 quad_perm:[2,3,0,1] row_mask:0xf bank_mask:0xf bound_ctrl:1
	v_add_f32_dpp v150, v150, v150 quad_perm:[2,3,0,1] row_mask:0xf bank_mask:0xf bound_ctrl:1
	s_nop 0
	v_mov_b32_dpp v149, v148 row_half_mirror row_mask:0xf bank_mask:0xf bound_ctrl:1
	v_mov_b32_dpp v151, v150 row_half_mirror row_mask:0xf bank_mask:0xf bound_ctrl:1
	s_and_saveexec_b64 s[28:29], s[6:7]
	v_add_f32_e32 v150, v150, v151
	ds_write_b32 v219, v150
	s_or_b64 exec, exec, s[28:29]
	v_add_f32_e32 v148, v148, v149
	v_max_f32_e32 v148, 0x179abe15, v148
	v_rsq_f32_e32 v148, v148
	v_lshlrev_b32_e32 v156, 16, v123
	v_and_b32_e32 v157, 0xffff0000, v123
	v_mul_f32_e32 v149, 0x3fb8aa3b, v156
	v_lshlrev_b32_e32 v150, 16, v120
	v_and_b32_e32 v151, 0xffff0000, v120
	v_lshlrev_b32_e32 v152, 16, v121
	v_and_b32_e32 v153, 0xffff0000, v121
	v_lshlrev_b32_e32 v154, 16, v122
	v_and_b32_e32 v155, 0xffff0000, v122
	v_pk_mul_f32 v[140:141], v[140:141], v[148:149] op_sel_hi:[1,0]
	v_pk_mul_f32 v[142:143], v[142:143], v[148:149] op_sel_hi:[1,0]
	v_pk_mul_f32 v[144:145], v[144:145], v[148:149] op_sel_hi:[1,0]
	v_pk_mul_f32 v[146:147], v[146:147], v[148:149] op_sel_hi:[1,0]
	v_mul_f32_e32 v148, 0x3fb8aa3b, v157
	v_mul_f32_e32 v120, 0x3fb8aa3b, v150
	v_mul_f32_e32 v121, 0x3fb8aa3b, v151
	v_mul_f32_e32 v122, 0x3fb8aa3b, v152
	v_mul_f32_e32 v123, 0x3fb8aa3b, v153
	v_mul_f32_e32 v150, 0x3fb8aa3b, v154
	v_mul_f32_e32 v151, 0x3fb8aa3b, v155
	v_exp_f32_e32 v152, v149
	v_exp_f32_e32 v153, v148
	v_lshlrev_b32_e32 v148, 16, v104
	v_and_b32_e32 v149, 0xffff0000, v104
	v_lshlrev_b32_e32 v154, 16, v108
	v_and_b32_e32 v155, 0xffff0000, v108
	v_lshlrev_b32_e32 v104, 16, v105
	v_and_b32_e32 v105, 0xffff0000, v105
	v_lshlrev_b32_e32 v108, 16, v109
	v_and_b32_e32 v109, 0xffff0000, v109
	v_pk_add_f32 v[108:109], v[108:109], v[104:105] neg_lo:[0,1] neg_hi:[0,1]
	v_exp_f32_e32 v120, v120
	v_pk_fma_f32 v[156:157], v[18:19], v[108:109], v[104:105]
	v_lshlrev_b32_e32 v104, 16, v106
	v_and_b32_e32 v105, 0xffff0000, v106
	v_lshlrev_b32_e32 v108, 16, v110
	v_and_b32_e32 v109, 0xffff0000, v110
	v_pk_add_f32 v[108:109], v[108:109], v[104:105] neg_lo:[0,1] neg_hi:[0,1]
	v_lshlrev_b32_e32 v106, 16, v107
	v_pk_fma_f32 v[104:105], v[20:21], v[108:109], v[104:105]
	v_and_b32_e32 v107, 0xffff0000, v107
	v_lshlrev_b32_e32 v108, 16, v111
	v_and_b32_e32 v109, 0xffff0000, v111
	v_exp_f32_e32 v121, v121
	v_exp_f32_e32 v122, v122
	v_exp_f32_e32 v123, v123
	v_pk_add_f32 v[108:109], v[108:109], v[106:107] neg_lo:[0,1] neg_hi:[0,1]
	v_exp_f32_e32 v150, v150
	v_exp_f32_e32 v151, v151
	v_pk_fma_f32 v[106:107], v[22:23], v[108:109], v[106:107]
	v_pk_mul_f32 v[108:109], v[140:141], v[128:129]
	v_pk_mul_f32 v[110:111], v[142:143], v[130:131]
	v_pk_add_f32 v[154:155], v[154:155], v[148:149] neg_lo:[0,1] neg_hi:[0,1]
	ds_write_b128 v193, v[136:139]
	ds_write_b128 v193, v[124:127] offset:16
	ds_write_b128 v193, v[120:123] offset:16384
	ds_write_b128 v193, v[150:153] offset:16400
	ds_write_b128 v193, v[112:115] offset:32768
	ds_write_b128 v193, v[116:119] offset:32784
	ds_write_b128 v193, v[140:143] offset:49152
	ds_write_b128 v193, v[144:147] offset:49168
	ds_write_b128 v204, v[108:111]
	v_pk_mul_f32 v[108:109], v[144:145], v[132:133]
	v_pk_mul_f32 v[110:111], v[146:147], v[134:135]
	v_mov_b32_e32 v224, 0
	v_pk_fma_f32 v[154:155], v[16:17], v[154:155], v[148:149]
	ds_write_b128 v204, v[108:111] offset:16
	ds_write_b128 v212, v[154:157]
	ds_write_b128 v212, v[104:107] offset:16
	s_waitcnt lgkmcnt(0)
	s_barrier
	s_mov_b32 s27, 0
	v_mov_b32_e32 v222, v177
	v_mov_b32_e32 v223, v197
	v_mov_b32_e32 v226, v216
	v_add_u32_e32 v227, 0x8000, v217
	ds_read_b128 v[112:115], v222 offset:49152
	ds_read_b128 v[116:119], v222 offset:49168
	ds_read_b128 v[136:139], v222 offset:0
	ds_read_b128 v[140:143], v222 offset:16
	ds_read_b128 v[120:123], v223 offset:0
	ds_read_b128 v[124:127], v223 offset:16
	ds_read_b128 v[128:131], v222 offset:32768
	ds_read_b128 v[132:135], v222 offset:32784
	ds_read_b32 v144, v226 offset:0
	ds_read_b128 v[104:107], v222 offset:16384
	ds_read_b128 v[108:111], v222 offset:16400
	v_mov_b32_e32 v224, 0
.Lrwkv_scan_loop:
	s_waitcnt lgkmcnt(7)
	v_pk_mul_f32 v[148:149], v[184:185], v[112:113]
	v_pk_mul_f32 v[156:157], v[184:185], v[136:137]
	v_pk_fma_f32 v[148:149], v[186:187], v[114:115], v[148:149]
	v_pk_fma_f32 v[156:157], v[186:187], v[138:139], v[156:157]
	v_pk_fma_f32 v[148:149], v[188:189], v[116:117], v[148:149]
	v_pk_fma_f32 v[156:157], v[188:189], v[140:141], v[156:157]
	v_pk_fma_f32 v[148:149], v[190:191], v[118:119], v[148:149]
	v_pk_fma_f32 v[156:157], v[190:191], v[142:143], v[156:157]
	v_add_f32_e32 v152, v148, v149
	v_add_f32_e32 v153, v156, v157
	ds_read_b128 v[112:115], v222 offset:49408
	v_add_f32_dpp v152, v152, v152 quad_perm:[1,0,3,2] row_mask:0xf bank_mask:0xf bound_ctrl:1
	v_add_f32_dpp v153, v153, v153 quad_perm:[1,0,3,2] row_mask:0xf bank_mask:0xf bound_ctrl:1
	ds_read_b128 v[116:119], v222 offset:49424
	v_add_f32_dpp v152, v152, v152 quad_perm:[2,3,0,1] row_mask:0xf bank_mask:0xf bound_ctrl:1
	v_add_f32_dpp v153, v153, v153 quad_perm:[2,3,0,1] row_mask:0xf bank_mask:0xf bound_ctrl:1
	ds_read_b128 v[136:139], v222 offset:0
	v_add_f32_dpp v152, v152, v152 row_half_mirror row_mask:0xf bank_mask:0xf bound_ctrl:1
	v_add_f32_dpp v153, v153, v153 row_half_mirror row_mask:0xf bank_mask:0xf bound_ctrl:1
	ds_read_b128 v[140:143], v222 offset:16
	v_cndmask_b32_e64 v224, v224, v153, s[8:9]
	ds_write_b32 v227, v224
	s_waitcnt lgkmcnt(9)
	v_pk_mul_f32 v[160:161], v[120:121], v[152:153] op_sel_hi:[1,0] neg_lo:[0,1] neg_hi:[0,1]
	v_pk_mul_f32 v[162:163], v[122:123], v[152:153] op_sel_hi:[1,0] neg_lo:[0,1] neg_hi:[0,1]
	v_pk_mul_f32 v[164:165], v[124:125], v[152:153] op_sel_hi:[1,0] neg_lo:[0,1] neg_hi:[0,1]
	v_pk_mul_f32 v[166:167], v[126:127], v[152:153] op_sel_hi:[1,0] neg_lo:[0,1] neg_hi:[0,1]
	ds_read_b128 v[120:123], v223 offset:256
	ds_read_b128 v[124:127], v223 offset:272
	v_add_u32_e32 v227, s27, v217
	s_waitcnt lgkmcnt(8)
	v_pk_fma_f32 v[160:161], v[144:145], v[128:129], v[160:161] op_sel_hi:[0,1,1]
	v_pk_fma_f32 v[162:163], v[144:145], v[130:131], v[162:163] op_sel_hi:[0,1,1]
	v_pk_fma_f32 v[164:165], v[144:145], v[132:133], v[164:165] op_sel_hi:[0,1,1]
	v_pk_fma_f32 v[166:167], v[144:145], v[134:135], v[166:167] op_sel_hi:[0,1,1]
	ds_read_b128 v[128:131], v222 offset:33024
	ds_read_b128 v[132:135], v222 offset:33040
	ds_read_b32 v144, v226 offset:256
	s_waitcnt lgkmcnt(9)
	v_pk_fma_f32 v[184:185], v[184:185], v[104:105], v[160:161]
	v_pk_fma_f32 v[186:187], v[186:187], v[106:107], v[162:163]
	v_pk_fma_f32 v[188:189], v[188:189], v[108:109], v[164:165]
	v_pk_fma_f32 v[190:191], v[190:191], v[110:111], v[166:167]
	ds_read_b128 v[104:107], v222 offset:16640
	ds_read_b128 v[108:111], v222 offset:16656
	s_waitcnt lgkmcnt(7)
	v_pk_mul_f32 v[148:149], v[184:185], v[112:113]
	v_pk_mul_f32 v[156:157], v[184:185], v[136:137]
	v_pk_fma_f32 v[148:149], v[186:187], v[114:115], v[148:149]
	v_pk_fma_f32 v[156:157], v[186:187], v[138:139], v[156:157]
	v_pk_fma_f32 v[148:149], v[188:189], v[116:117], v[148:149]
	v_pk_fma_f32 v[156:157], v[188:189], v[140:141], v[156:157]
	v_pk_fma_f32 v[148:149], v[190:191], v[118:119], v[148:149]
	v_pk_fma_f32 v[156:157], v[190:191], v[142:143], v[156:157]
	v_add_f32_e32 v152, v148, v149
	v_add_f32_e32 v153, v156, v157
	ds_read_b128 v[112:115], v222 offset:49664
	v_add_f32_dpp v152, v152, v152 quad_perm:[1,0,3,2] row_mask:0xf bank_mask:0xf bound_ctrl:1
	v_add_f32_dpp v153, v153, v153 quad_perm:[1,0,3,2] row_mask:0xf bank_mask:0xf bound_ctrl:1
	ds_read_b128 v[116:119], v222 offset:49680
	v_add_f32_dpp v152, v152, v152 quad_perm:[2,3,0,1] row_mask:0xf bank_mask:0xf bound_ctrl:1
	v_add_f32_dpp v153, v153, v153 quad_perm:[2,3,0,1] row_mask:0xf bank_mask:0xf bound_ctrl:1
	ds_read_b128 v[136:139], v222 offset:256
	v_add_f32_dpp v152, v152, v152 row_half_mirror row_mask:0xf bank_mask:0xf bound_ctrl:1
	v_add_f32_dpp v153, v153, v153 row_half_mirror row_mask:0xf bank_mask:0xf bound_ctrl:1
	ds_read_b128 v[140:143], v222 offset:272
	v_cndmask_b32_e64 v224, v224, v153, s[6:7]
	s_waitcnt lgkmcnt(9)
	v_pk_mul_f32 v[160:161], v[120:121], v[152:153] op_sel_hi:[1,0] neg_lo:[0,1] neg_hi:[0,1]
	v_pk_mul_f32 v[162:163], v[122:123], v[152:153] op_sel_hi:[1,0] neg_lo:[0,1] neg_hi:[0,1]
	v_pk_mul_f32 v[164:165], v[124:125], v[152:153] op_sel_hi:[1,0] neg_lo:[0,1] neg_hi:[0,1]
	v_pk_mul_f32 v[166:167], v[126:127], v[152:153] op_sel_hi:[1,0] neg_lo:[0,1] neg_hi:[0,1]
	ds_read_b128 v[120:123], v223 offset:512
	ds_read_b128 v[124:127], v223 offset:528
	s_waitcnt lgkmcnt(8)
	v_pk_fma_f32 v[160:161], v[144:145], v[128:129], v[160:161] op_sel_hi:[0,1,1]
	v_pk_fma_f32 v[162:163], v[144:145], v[130:131], v[162:163] op_sel_hi:[0,1,1]
	v_pk_fma_f32 v[164:165], v[144:145], v[132:133], v[164:165] op_sel_hi:[0,1,1]
	v_pk_fma_f32 v[166:167], v[144:145], v[134:135], v[166:167] op_sel_hi:[0,1,1]
	ds_read_b128 v[128:131], v222 offset:33280
	ds_read_b128 v[132:135], v222 offset:33296
	ds_read_b32 v144, v226 offset:512
	s_waitcnt lgkmcnt(9)
	v_pk_fma_f32 v[184:185], v[184:185], v[104:105], v[160:161]
	v_pk_fma_f32 v[186:187], v[186:187], v[106:107], v[162:163]
	v_pk_fma_f32 v[188:189], v[188:189], v[108:109], v[164:165]
	v_pk_fma_f32 v[190:191], v[190:191], v[110:111], v[166:167]
	ds_read_b128 v[104:107], v222 offset:16896
	ds_read_b128 v[108:111], v222 offset:16912
	s_waitcnt lgkmcnt(7)
	v_pk_mul_f32 v[148:149], v[184:185], v[112:113]
	v_pk_mul_f32 v[156:157], v[184:185], v[136:137]
	v_pk_fma_f32 v[148:149], v[186:187], v[114:115], v[148:149]
	v_pk_fma_f32 v[156:157], v[186:187], v[138:139], v[156:157]
	v_pk_fma_f32 v[148:149], v[188:189], v[116:117], v[148:149]
	v_pk_fma_f32 v[156:157], v[188:189], v[140:141], v[156:157]
	v_pk_fma_f32 v[148:149], v[190:191], v[118:119], v[148:149]
	v_pk_fma_f32 v[156:157], v[190:191], v[142:143], v[156:157]
	v_add_f32_e32 v152, v148, v149
	v_add_f32_e32 v153, v156, v157
	ds_read_b128 v[112:115], v222 offset:49920
	v_add_f32_dpp v152, v152, v152 quad_perm:[1,0,3,2] row_mask:0xf bank_mask:0xf bound_ctrl:1
	v_add_f32_dpp v153, v153, v153 quad_perm:[1,0,3,2] row_mask:0xf bank_mask:0xf bound_ctrl:1
	ds_read_b128 v[116:119], v222 offset:49936
	v_add_f32_dpp v152, v152, v152 quad_perm:[2,3,0,1] row_mask:0xf bank_mask:0xf bound_ctrl:1
	v_add_f32_dpp v153, v153, v153 quad_perm:[2,3,0,1] row_mask:0xf bank_mask:0xf bound_ctrl:1
	ds_read_b128 v[136:139], v222 offset:512
	v_add_f32_dpp v152, v152, v152 row_half_mirror row_mask:0xf bank_mask:0xf bound_ctrl:1
	v_add_f32_dpp v153, v153, v153 row_half_mirror row_mask:0xf bank_mask:0xf bound_ctrl:1
	ds_read_b128 v[140:143], v222 offset:528
	v_cndmask_b32_e64 v224, v224, v153, s[10:11]
	s_waitcnt lgkmcnt(9)
	v_pk_mul_f32 v[160:161], v[120:121], v[152:153] op_sel_hi:[1,0] neg_lo:[0,1] neg_hi:[0,1]
	v_pk_mul_f32 v[162:163], v[122:123], v[152:153] op_sel_hi:[1,0] neg_lo:[0,1] neg_hi:[0,1]
	v_pk_mul_f32 v[164:165], v[124:125], v[152:153] op_sel_hi:[1,0] neg_lo:[0,1] neg_hi:[0,1]
	v_pk_mul_f32 v[166:167], v[126:127], v[152:153] op_sel_hi:[1,0] neg_lo:[0,1] neg_hi:[0,1]
	ds_read_b128 v[120:123], v223 offset:768
	ds_read_b128 v[124:127], v223 offset:784
	s_waitcnt lgkmcnt(8)
	v_pk_fma_f32 v[160:161], v[144:145], v[128:129], v[160:161] op_sel_hi:[0,1,1]
	v_pk_fma_f32 v[162:163], v[144:145], v[130:131], v[162:163] op_sel_hi:[0,1,1]
	v_pk_fma_f32 v[164:165], v[144:145], v[132:133], v[164:165] op_sel_hi:[0,1,1]
	v_pk_fma_f32 v[166:167], v[144:145], v[134:135], v[166:167] op_sel_hi:[0,1,1]
	ds_read_b128 v[128:131], v222 offset:33536
	ds_read_b128 v[132:135], v222 offset:33552
	ds_read_b32 v144, v226 offset:768
	s_waitcnt lgkmcnt(9)
	v_pk_fma_f32 v[184:185], v[184:185], v[104:105], v[160:161]
	v_pk_fma_f32 v[186:187], v[186:187], v[106:107], v[162:163]
	v_pk_fma_f32 v[188:189], v[188:189], v[108:109], v[164:165]
	v_pk_fma_f32 v[190:191], v[190:191], v[110:111], v[166:167]
	ds_read_b128 v[104:107], v222 offset:17152
	ds_read_b128 v[108:111], v222 offset:17168
	s_waitcnt lgkmcnt(7)
	v_pk_mul_f32 v[148:149], v[184:185], v[112:113]
	v_pk_mul_f32 v[156:157], v[184:185], v[136:137]
	v_pk_fma_f32 v[148:149], v[186:187], v[114:115], v[148:149]
	v_pk_fma_f32 v[156:157], v[186:187], v[138:139], v[156:157]
	v_pk_fma_f32 v[148:149], v[188:189], v[116:117], v[148:149]
	v_pk_fma_f32 v[156:157], v[188:189], v[140:141], v[156:157]
	v_pk_fma_f32 v[148:149], v[190:191], v[118:119], v[148:149]
	v_pk_fma_f32 v[156:157], v[190:191], v[142:143], v[156:157]
	v_add_f32_e32 v152, v148, v149
	v_add_f32_e32 v153, v156, v157
	ds_read_b128 v[112:115], v222 offset:50176
	v_add_f32_dpp v152, v152, v152 quad_perm:[1,0,3,2] row_mask:0xf bank_mask:0xf bound_ctrl:1
	v_add_f32_dpp v153, v153, v153 quad_perm:[1,0,3,2] row_mask:0xf bank_mask:0xf bound_ctrl:1
	ds_read_b128 v[116:119], v222 offset:50192
	v_add_f32_dpp v152, v152, v152 quad_perm:[2,3,0,1] row_mask:0xf bank_mask:0xf bound_ctrl:1
	v_add_f32_dpp v153, v153, v153 quad_perm:[2,3,0,1] row_mask:0xf bank_mask:0xf bound_ctrl:1
	ds_read_b128 v[136:139], v222 offset:768
	v_add_f32_dpp v152, v152, v152 row_half_mirror row_mask:0xf bank_mask:0xf bound_ctrl:1
	v_add_f32_dpp v153, v153, v153 row_half_mirror row_mask:0xf bank_mask:0xf bound_ctrl:1
	ds_read_b128 v[140:143], v222 offset:784
	v_cndmask_b32_e64 v224, v224, v153, s[12:13]
	s_waitcnt lgkmcnt(9)
	v_pk_mul_f32 v[160:161], v[120:121], v[152:153] op_sel_hi:[1,0] neg_lo:[0,1] neg_hi:[0,1]
	v_pk_mul_f32 v[162:163], v[122:123], v[152:153] op_sel_hi:[1,0] neg_lo:[0,1] neg_hi:[0,1]
	v_pk_mul_f32 v[164:165], v[124:125], v[152:153] op_sel_hi:[1,0] neg_lo:[0,1] neg_hi:[0,1]
	v_pk_mul_f32 v[166:167], v[126:127], v[152:153] op_sel_hi:[1,0] neg_lo:[0,1] neg_hi:[0,1]
	ds_read_b128 v[120:123], v223 offset:1024
	ds_read_b128 v[124:127], v223 offset:1040
	s_waitcnt lgkmcnt(8)
	v_pk_fma_f32 v[160:161], v[144:145], v[128:129], v[160:161] op_sel_hi:[0,1,1]
	v_pk_fma_f32 v[162:163], v[144:145], v[130:131], v[162:163] op_sel_hi:[0,1,1]
	v_pk_fma_f32 v[164:165], v[144:145], v[132:133], v[164:165] op_sel_hi:[0,1,1]
	v_pk_fma_f32 v[166:167], v[144:145], v[134:135], v[166:167] op_sel_hi:[0,1,1]
	ds_read_b128 v[128:131], v222 offset:33792
	ds_read_b128 v[132:135], v222 offset:33808
	ds_read_b32 v144, v226 offset:1024
	s_waitcnt lgkmcnt(9)
	v_pk_fma_f32 v[184:185], v[184:185], v[104:105], v[160:161]
	v_pk_fma_f32 v[186:187], v[186:187], v[106:107], v[162:163]
	v_pk_fma_f32 v[188:189], v[188:189], v[108:109], v[164:165]
	v_pk_fma_f32 v[190:191], v[190:191], v[110:111], v[166:167]
	ds_read_b128 v[104:107], v222 offset:17408
	ds_read_b128 v[108:111], v222 offset:17424
	s_waitcnt lgkmcnt(7)
	v_pk_mul_f32 v[148:149], v[184:185], v[112:113]
	v_pk_mul_f32 v[156:157], v[184:185], v[136:137]
	v_pk_fma_f32 v[148:149], v[186:187], v[114:115], v[148:149]
	v_pk_fma_f32 v[156:157], v[186:187], v[138:139], v[156:157]
	v_pk_fma_f32 v[148:149], v[188:189], v[116:117], v[148:149]
	v_pk_fma_f32 v[156:157], v[188:189], v[140:141], v[156:157]
	v_pk_fma_f32 v[148:149], v[190:191], v[118:119], v[148:149]
	v_pk_fma_f32 v[156:157], v[190:191], v[142:143], v[156:157]
	v_add_f32_e32 v152, v148, v149
	v_add_f32_e32 v153, v156, v157
	ds_read_b128 v[112:115], v222 offset:50432
	v_add_f32_dpp v152, v152, v152 quad_perm:[1,0,3,2] row_mask:0xf bank_mask:0xf bound_ctrl:1
	v_add_f32_dpp v153, v153, v153 quad_perm:[1,0,3,2] row_mask:0xf bank_mask:0xf bound_ctrl:1
	ds_read_b128 v[116:119], v222 offset:50448
	v_add_f32_dpp v152, v152, v152 quad_perm:[2,3,0,1] row_mask:0xf bank_mask:0xf bound_ctrl:1
	v_add_f32_dpp v153, v153, v153 quad_perm:[2,3,0,1] row_mask:0xf bank_mask:0xf bound_ctrl:1
	ds_read_b128 v[136:139], v222 offset:1024
	v_add_f32_dpp v152, v152, v152 row_half_mirror row_mask:0xf bank_mask:0xf bound_ctrl:1
	v_add_f32_dpp v153, v153, v153 row_half_mirror row_mask:0xf bank_mask:0xf bound_ctrl:1
	ds_read_b128 v[140:143], v222 offset:1040
	v_cndmask_b32_e64 v224, v224, v153, s[14:15]
	s_waitcnt lgkmcnt(9)
	v_pk_mul_f32 v[160:161], v[120:121], v[152:153] op_sel_hi:[1,0] neg_lo:[0,1] neg_hi:[0,1]
	v_pk_mul_f32 v[162:163], v[122:123], v[152:153] op_sel_hi:[1,0] neg_lo:[0,1] neg_hi:[0,1]
	v_pk_mul_f32 v[164:165], v[124:125], v[152:153] op_sel_hi:[1,0] neg_lo:[0,1] neg_hi:[0,1]
	v_pk_mul_f32 v[166:167], v[126:127], v[152:153] op_sel_hi:[1,0] neg_lo:[0,1] neg_hi:[0,1]
	ds_read_b128 v[120:123], v223 offset:1280
	ds_read_b128 v[124:127], v223 offset:1296
	s_waitcnt lgkmcnt(8)
	v_pk_fma_f32 v[160:161], v[144:145], v[128:129], v[160:161] op_sel_hi:[0,1,1]
	v_pk_fma_f32 v[162:163], v[144:145], v[130:131], v[162:163] op_sel_hi:[0,1,1]
	v_pk_fma_f32 v[164:165], v[144:145], v[132:133], v[164:165] op_sel_hi:[0,1,1]
	v_pk_fma_f32 v[166:167], v[144:145], v[134:135], v[166:167] op_sel_hi:[0,1,1]
	ds_read_b128 v[128:131], v222 offset:34048
	ds_read_b128 v[132:135], v222 offset:34064
	ds_read_b32 v144, v226 offset:1280
	s_waitcnt lgkmcnt(9)
	v_pk_fma_f32 v[184:185], v[184:185], v[104:105], v[160:161]
	v_pk_fma_f32 v[186:187], v[186:187], v[106:107], v[162:163]
	v_pk_fma_f32 v[188:189], v[188:189], v[108:109], v[164:165]
	v_pk_fma_f32 v[190:191], v[190:191], v[110:111], v[166:167]
	ds_read_b128 v[104:107], v222 offset:17664
	ds_read_b128 v[108:111], v222 offset:17680
	s_waitcnt lgkmcnt(7)
	v_pk_mul_f32 v[148:149], v[184:185], v[112:113]
	v_pk_mul_f32 v[156:157], v[184:185], v[136:137]
	v_pk_fma_f32 v[148:149], v[186:187], v[114:115], v[148:149]
	v_pk_fma_f32 v[156:157], v[186:187], v[138:139], v[156:157]
	v_pk_fma_f32 v[148:149], v[188:189], v[116:117], v[148:149]
	v_pk_fma_f32 v[156:157], v[188:189], v[140:141], v[156:157]
	v_pk_fma_f32 v[148:149], v[190:191], v[118:119], v[148:149]
	v_pk_fma_f32 v[156:157], v[190:191], v[142:143], v[156:157]
	v_add_f32_e32 v152, v148, v149
	v_add_f32_e32 v153, v156, v157
	ds_read_b128 v[112:115], v222 offset:50688
	v_add_f32_dpp v152, v152, v152 quad_perm:[1,0,3,2] row_mask:0xf bank_mask:0xf bound_ctrl:1
	v_add_f32_dpp v153, v153, v153 quad_perm:[1,0,3,2] row_mask:0xf bank_mask:0xf bound_ctrl:1
	ds_read_b128 v[116:119], v222 offset:50704
	v_add_f32_dpp v152, v152, v152 quad_perm:[2,3,0,1] row_mask:0xf bank_mask:0xf bound_ctrl:1
	v_add_f32_dpp v153, v153, v153 quad_perm:[2,3,0,1] row_mask:0xf bank_mask:0xf bound_ctrl:1
	ds_read_b128 v[136:139], v222 offset:1280
	v_add_f32_dpp v152, v152, v152 row_half_mirror row_mask:0xf bank_mask:0xf bound_ctrl:1
	v_add_f32_dpp v153, v153, v153 row_half_mirror row_mask:0xf bank_mask:0xf bound_ctrl:1
	ds_read_b128 v[140:143], v222 offset:1296
	v_cndmask_b32_e64 v224, v224, v153, s[16:17]
	s_waitcnt lgkmcnt(9)
	v_pk_mul_f32 v[160:161], v[120:121], v[152:153] op_sel_hi:[1,0] neg_lo:[0,1] neg_hi:[0,1]
	v_pk_mul_f32 v[162:163], v[122:123], v[152:153] op_sel_hi:[1,0] neg_lo:[0,1] neg_hi:[0,1]
	v_pk_mul_f32 v[164:165], v[124:125], v[152:153] op_sel_hi:[1,0] neg_lo:[0,1] neg_hi:[0,1]
	v_pk_mul_f32 v[166:167], v[126:127], v[152:153] op_sel_hi:[1,0] neg_lo:[0,1] neg_hi:[0,1]
	ds_read_b128 v[120:123], v223 offset:1536
	ds_read_b128 v[124:127], v223 offset:1552
	s_waitcnt lgkmcnt(8)
	v_pk_fma_f32 v[160:161], v[144:145], v[128:129], v[160:161] op_sel_hi:[0,1,1]
	v_pk_fma_f32 v[162:163], v[144:145], v[130:131], v[162:163] op_sel_hi:[0,1,1]
	v_pk_fma_f32 v[164:165], v[144:145], v[132:133], v[164:165] op_sel_hi:[0,1,1]
	v_pk_fma_f32 v[166:167], v[144:145], v[134:135], v[166:167] op_sel_hi:[0,1,1]
	ds_read_b128 v[128:131], v222 offset:34304
	ds_read_b128 v[132:135], v222 offset:34320
	ds_read_b32 v144, v226 offset:1536
	s_waitcnt lgkmcnt(9)
	v_pk_fma_f32 v[184:185], v[184:185], v[104:105], v[160:161]
	v_pk_fma_f32 v[186:187], v[186:187], v[106:107], v[162:163]
	v_pk_fma_f32 v[188:189], v[188:189], v[108:109], v[164:165]
	v_pk_fma_f32 v[190:191], v[190:191], v[110:111], v[166:167]
	ds_read_b128 v[104:107], v222 offset:17920
	ds_read_b128 v[108:111], v222 offset:17936
	s_waitcnt lgkmcnt(7)
	v_pk_mul_f32 v[148:149], v[184:185], v[112:113]
	v_pk_mul_f32 v[156:157], v[184:185], v[136:137]
	v_pk_fma_f32 v[148:149], v[186:187], v[114:115], v[148:149]
	v_pk_fma_f32 v[156:157], v[186:187], v[138:139], v[156:157]
	v_pk_fma_f32 v[148:149], v[188:189], v[116:117], v[148:149]
	v_pk_fma_f32 v[156:157], v[188:189], v[140:141], v[156:157]
	v_pk_fma_f32 v[148:149], v[190:191], v[118:119], v[148:149]
	v_pk_fma_f32 v[156:157], v[190:191], v[142:143], v[156:157]
	v_add_f32_e32 v152, v148, v149
	v_add_f32_e32 v153, v156, v157
	ds_read_b128 v[112:115], v222 offset:50944
	v_add_f32_dpp v152, v152, v152 quad_perm:[1,0,3,2] row_mask:0xf bank_mask:0xf bound_ctrl:1
	v_add_f32_dpp v153, v153, v153 quad_perm:[1,0,3,2] row_mask:0xf bank_mask:0xf bound_ctrl:1
	ds_read_b128 v[116:119], v222 offset:50960
	v_add_f32_dpp v152, v152, v152 quad_perm:[2,3,0,1] row_mask:0xf bank_mask:0xf bound_ctrl:1
	v_add_f32_dpp v153, v153, v153 quad_perm:[2,3,0,1] row_mask:0xf bank_mask:0xf bound_ctrl:1
	ds_read_b128 v[136:139], v222 offset:1536
	v_add_f32_dpp v152, v152, v152 row_half_mirror row_mask:0xf bank_mask:0xf bound_ctrl:1
	v_add_f32_dpp v153, v153, v153 row_half_mirror row_mask:0xf bank_mask:0xf bound_ctrl:1
	ds_read_b128 v[140:143], v222 offset:1552
	v_cndmask_b32_e64 v224, v224, v153, s[18:19]
	s_waitcnt lgkmcnt(9)
	v_pk_mul_f32 v[160:161], v[120:121], v[152:153] op_sel_hi:[1,0] neg_lo:[0,1] neg_hi:[0,1]
	v_pk_mul_f32 v[162:163], v[122:123], v[152:153] op_sel_hi:[1,0] neg_lo:[0,1] neg_hi:[0,1]
	v_pk_mul_f32 v[164:165], v[124:125], v[152:153] op_sel_hi:[1,0] neg_lo:[0,1] neg_hi:[0,1]
	v_pk_mul_f32 v[166:167], v[126:127], v[152:153] op_sel_hi:[1,0] neg_lo:[0,1] neg_hi:[0,1]
	ds_read_b128 v[120:123], v223 offset:1792
	ds_read_b128 v[124:127], v223 offset:1808
	s_waitcnt lgkmcnt(8)
	v_pk_fma_f32 v[160:161], v[144:145], v[128:129], v[160:161] op_sel_hi:[0,1,1]
	v_pk_fma_f32 v[162:163], v[144:145], v[130:131], v[162:163] op_sel_hi:[0,1,1]
	v_pk_fma_f32 v[164:165], v[144:145], v[132:133], v[164:165] op_sel_hi:[0,1,1]
	v_pk_fma_f32 v[166:167], v[144:145], v[134:135], v[166:167] op_sel_hi:[0,1,1]
	ds_read_b128 v[128:131], v222 offset:34560
	ds_read_b128 v[132:135], v222 offset:34576
	ds_read_b32 v144, v226 offset:1792
	s_waitcnt lgkmcnt(9)
	v_pk_fma_f32 v[184:185], v[184:185], v[104:105], v[160:161]
	v_pk_fma_f32 v[186:187], v[186:187], v[106:107], v[162:163]
	v_pk_fma_f32 v[188:189], v[188:189], v[108:109], v[164:165]
	v_pk_fma_f32 v[190:191], v[190:191], v[110:111], v[166:167]
	ds_read_b128 v[104:107], v222 offset:18176
	ds_read_b128 v[108:111], v222 offset:18192
	s_waitcnt lgkmcnt(7)
	v_pk_mul_f32 v[148:149], v[184:185], v[112:113]
	v_pk_mul_f32 v[156:157], v[184:185], v[136:137]
	v_pk_fma_f32 v[148:149], v[186:187], v[114:115], v[148:149]
	v_pk_fma_f32 v[156:157], v[186:187], v[138:139], v[156:157]
	v_pk_fma_f32 v[148:149], v[188:189], v[116:117], v[148:149]
	v_pk_fma_f32 v[156:157], v[188:189], v[140:141], v[156:157]
	v_pk_fma_f32 v[148:149], v[190:191], v[118:119], v[148:149]
	v_pk_fma_f32 v[156:157], v[190:191], v[142:143], v[156:157]
	v_add_f32_e32 v152, v148, v149
	v_add_f32_e32 v153, v156, v157
	ds_read_b128 v[112:115], v222 offset:51200
	v_add_f32_dpp v152, v152, v152 quad_perm:[1,0,3,2] row_mask:0xf bank_mask:0xf bound_ctrl:1
	v_add_f32_dpp v153, v153, v153 quad_perm:[1,0,3,2] row_mask:0xf bank_mask:0xf bound_ctrl:1
	ds_read_b128 v[116:119], v222 offset:51216
	v_add_f32_dpp v152, v152, v152 quad_perm:[2,3,0,1] row_mask:0xf bank_mask:0xf bound_ctrl:1
	v_add_f32_dpp v153, v153, v153 quad_perm:[2,3,0,1] row_mask:0xf bank_mask:0xf bound_ctrl:1
	ds_read_b128 v[136:139], v222 offset:1792
	v_add_f32_dpp v152, v152, v152 row_half_mirror row_mask:0xf bank_mask:0xf bound_ctrl:1
	v_add_f32_dpp v153, v153, v153 row_half_mirror row_mask:0xf bank_mask:0xf bound_ctrl:1
	ds_read_b128 v[140:143], v222 offset:1808
	v_cndmask_b32_e64 v224, v224, v153, s[20:21]
	s_waitcnt lgkmcnt(9)
	v_pk_mul_f32 v[160:161], v[120:121], v[152:153] op_sel_hi:[1,0] neg_lo:[0,1] neg_hi:[0,1]
	v_pk_mul_f32 v[162:163], v[122:123], v[152:153] op_sel_hi:[1,0] neg_lo:[0,1] neg_hi:[0,1]
	v_pk_mul_f32 v[164:165], v[124:125], v[152:153] op_sel_hi:[1,0] neg_lo:[0,1] neg_hi:[0,1]
	v_pk_mul_f32 v[166:167], v[126:127], v[152:153] op_sel_hi:[1,0] neg_lo:[0,1] neg_hi:[0,1]
	ds_read_b128 v[120:123], v223 offset:2048
	ds_read_b128 v[124:127], v223 offset:2064
	s_waitcnt lgkmcnt(8)
	v_pk_fma_f32 v[160:161], v[144:145], v[128:129], v[160:161] op_sel_hi:[0,1,1]
	v_pk_fma_f32 v[162:163], v[144:145], v[130:131], v[162:163] op_sel_hi:[0,1,1]
	v_pk_fma_f32 v[164:165], v[144:145], v[132:133], v[164:165] op_sel_hi:[0,1,1]
	v_pk_fma_f32 v[166:167], v[144:145], v[134:135], v[166:167] op_sel_hi:[0,1,1]
	ds_read_b128 v[128:131], v222 offset:34816
	ds_read_b128 v[132:135], v222 offset:34832
	ds_read_b32 v144, v226 offset:2048
	s_waitcnt lgkmcnt(9)
	v_pk_fma_f32 v[184:185], v[184:185], v[104:105], v[160:161]
	v_pk_fma_f32 v[186:187], v[186:187], v[106:107], v[162:163]
	v_pk_fma_f32 v[188:189], v[188:189], v[108:109], v[164:165]
	v_pk_fma_f32 v[190:191], v[190:191], v[110:111], v[166:167]
	ds_read_b128 v[104:107], v222 offset:18432
	ds_read_b128 v[108:111], v222 offset:18448
	s_addk_i32 s27, 0x800
	v_add_u32_e32 v222, s27, v177
	v_add_u32_e32 v223, s27, v197
	v_add_u32_e32 v226, s27, v216
	s_cmpk_lg_u32 s27, 0x4000
	s_cbranch_scc1 .Lrwkv_scan_loop
	s_waitcnt lgkmcnt(0)
	v_pk_mul_f32 v[156:157], v[184:185], v[136:137]
	s_nop 0
	v_pk_fma_f32 v[156:157], v[186:187], v[138:139], v[156:157]
	s_nop 0
	v_pk_fma_f32 v[156:157], v[188:189], v[140:141], v[156:157]
	s_nop 0
	v_pk_fma_f32 v[156:157], v[190:191], v[142:143], v[156:157]
	s_nop 0
	v_add_f32_e32 v153, v156, v157
	s_nop 1
	v_add_f32_dpp v153, v153, v153 quad_perm:[1,0,3,2] row_mask:0xf bank_mask:0xf bound_ctrl:1
	s_nop 1
	v_add_f32_dpp v153, v153, v153 quad_perm:[2,3,0,1] row_mask:0xf bank_mask:0xf bound_ctrl:1
	s_nop 1
	v_add_f32_dpp v153, v153, v153 row_half_mirror row_mask:0xf bank_mask:0xf bound_ctrl:1
	v_cndmask_b32_e64 v224, v224, v153, s[8:9]
	ds_write_b32 v227, v224
	s_waitcnt lgkmcnt(0)
	s_branch .LBB0_263
